# context-token attention/pool items executed early on the blocks idle in in-proj round 2 (per-group completion counter, 8x(2 ctx+1 pool)+2x(4 pool) split), phase B shortened to latent item + one pool i
# speedup vs baseline: 1.0358x; 1.0161x over previous
_Z14fwd_megakernel6Params:
	s_load_dwordx4 s[28:31], s[0:1], 0x90
	s_mov_b32 s99, 0
	s_load_dword s68, s[0:1], 0xa0
	s_add_u32 s6, s0, 0x98
	s_addc_u32 s7, s1, 0
	v_and_b32_e32 v1, 0x3ff, v0
	s_mov_b32 s85, s2
	s_movk_i32 s3, 0x3ff
	s_waitcnt lgkmcnt(0)
	s_cmp_lg_u64 s[28:29], 0
	v_readfirstlane_b32 s16, v1
	s_cbranch_scc1 .LBB0_12
	v_lshrrev_b32_e32 v2, 20, v0
	v_lshrrev_b32_e32 v0, 10, v0
	v_or_b32_e32 v0, v0, v2
	v_and_or_b32 v0, v0, s3, v1
	v_cmp_eq_u32_e32 vcc, 0, v0
	s_barrier
	s_and_saveexec_b64 s[4:5], vcc
	s_cbranch_execz .LBB0_11
	buffer_wbl2 sc1
	s_load_dwordx2 s[6:7], s[6:7], 0x58
	s_mov_b64 s[8:9], exec
	v_mbcnt_lo_u32_b32 v0, s8, 0
	v_mbcnt_hi_u32_b32 v0, s9, v0
	v_cmp_eq_u32_e32 vcc, 0, v0
	s_waitcnt lgkmcnt(0)
	s_load_dword s3, s[6:7], 0x28
	s_and_saveexec_b64 s[10:11], vcc
	s_cbranch_execz .LBB0_4
	s_bcnt1_i32_b64 s8, s[8:9]
	v_mov_b32_e32 v1, 0
	v_mov_b32_e32 v2, s8
	global_atomic_add v1, v1, v2, s[6:7] offset:32 sc0

.LBB0_190:
	s_ashr_i32 s12, s33, 3
	s_mul_hi_i32 s13, s12, 0x38e38e39
	s_lshr_b32 s23, s13, 31
	s_ashr_i32 s13, s13, 1
	s_add_i32 s13, s13, s23
	s_mul_i32 s23, s13, 9
	s_sub_i32 s23, s12, s23
	s_lshl_b32 s12, s33, 8
	s_waitcnt vmcnt(0) lgkmcnt(0)
	s_barrier
	s_cmpk_lt_i32 s33, 0x100
	s_cbranch_scc1 .Lsig_skip
	s_cmpk_ge_i32 s33, 0x190
	s_cbranch_scc1 .Lsig_skip
	s_cmp_lg_u32 s3, 0
	s_cbranch_scc1 .Lsig_skip
	s_mov_b64 s[92:93], exec
	s_mov_b64 exec, 1
	s_and_b32 s90, s85, 7
	s_lshl_b32 s90, s90, 8
	s_add_i32 s90, s90, 0xb8fc480
	v_mov_b32_e32 v0, s90
	v_mov_b32_e32 v1, 1
	global_atomic_add v0, v1, s[28:29]
	s_mov_b64 exec, s[92:93]
.Lsig_skip:
	v_mbcnt_lo_u32_b32 v0, -1, 0
	v_mbcnt_hi_u32_b32 v0, -1, v0
	s_lshl_b32 s63, s13, 11
	s_and_b32 s12, s12, 0x700
	v_add_u32_e32 v0, s3, v0
	s_movk_i32 s13, 0xff
	s_or_b32 s12, s63, s12
	s_lshl_b32 s88, s23, 8
	v_cmp_lt_i32_e32 vcc, s13, v0
	s_and_saveexec_b64 s[52:53], vcc
	s_xor_b64 s[52:53], exec, s[52:53]
	s_cbranch_execz .LBB0_192
	v_add_u32_e32 v10, 0xffffff00, v0
	v_add_u32_e32 v0, s12, v10
	v_ashrrev_i32_e32 v1, 31, v0
	v_lshlrev_b64 v[0:1], 5, v[0:1]
	v_lshl_add_u64 v[4:5], s[8:9], 0, v[0:1]
	global_load_dwordx4 v[0:3], v[4:5], off
	s_nop 0
	global_load_dwordx4 v[4:7], v[4:5], off offset:16
	s_mov_b32 s13, 0x800000
	s_ashr_i32 s89, s88, 31
	s_waitcnt vmcnt(1)
	v_mov_b32_e32 v8, v0
	s_waitcnt vmcnt(0)
	v_mov_b32_e32 v9, v4
	v_mov_b32_e32 v4, v1
	v_mov_b32_e32 v0, v2
	v_mov_b32_e32 v1, v6
	v_mov_b32_e32 v6, v3
	v_pk_add_f32 v[2:3], v[8:9], v[4:5]
	v_pk_add_f32 v[0:1], v[0:1], v[6:7]
	s_nop 0
	v_pk_add_f32 v[0:1], v[2:3], v[0:1]
	s_nop 0
	v_add_f32_e32 v0, v0, v1
	v_fmamk_f32 v0, v0, 0x3a800000, v196
	v_mul_f32_e32 v1, 0x4b800000, v0
	v_cmp_gt_f32_e32 vcc, s13, v0
	s_nop 1
	v_cndmask_b32_e32 v0, v0, v1, vcc
	v_rsq_f32_e32 v0, v0
	v_lshl_add_u32 v1, v10, 2, v248
	v_mul_f32_e32 v2, 0x45800000, v0
	v_cndmask_b32_e32 v0, v0, v2, vcc
	ds_write_b32 v1, v0

.LBB0_232:
	v_mov_b32_e32 v0, 0x23808
	ds_read_b32 v0, v0
	s_waitcnt lgkmcnt(0)
	v_readfirstlane_b32 s98, v0
	s_cmp_eq_u32 s98, 0
	s_cbranch_scc1 .Lemi_skip
	s_cmpk_lt_i32 s85, 0xb0
	s_cbranch_scc1 .Lemi_skip
	s_waitcnt vmcnt(0)
	s_cmp_lg_u32 s3, 0
	s_cbranch_scc1 .Lemi_nopoll
	s_mov_b64 s[10:11], exec
	s_mov_b64 exec, 1
	s_and_b32 s4, s85, 7
	s_lshl_b32 s4, s4, 8
	s_add_i32 s4, s4, 0xb8fc480
	v_mov_b32_e32 v0, s4
	s_add_i32 s5, s86, 1
	s_mul_i32 s5, s5, 18
	v_mov_b32_e32 v1, s5
	s_mov_b32 s6, 0
.Lemi_spin:
	global_load_dword v2, v0, s[28:29] sc1
	s_waitcnt vmcnt(0)
	v_cmp_ge_u32_e32 vcc, v2, v1
	s_cbranch_vccnz .Lemi_got
	s_sleep 1
	s_add_i32 s6, s6, 1
	s_cmp_lt_u32 s6, 0x8000
	s_cbranch_scc1 .Lemi_spin
.Lemi_got:
	buffer_inv sc1
	s_waitcnt vmcnt(0)
	s_mov_b64 exec, s[10:11]
.Lemi_nopoll:
	s_barrier
	s_mov_b32 s99, 1
	s_lshr_b32 s101, s85, 3
	s_sub_i32 s101, s101, 22
	s_lshl_b32 s100, s101, 1
	s_add_i32 s98, s100, 1
	s_lshl_b32 s98, s98, 6
	s_or_b32 s100, s100, s98
	s_add_i32 s98, s101, 16
	s_lshl_b32 s98, s98, 12
	s_or_b32 s100, s100, s98
	s_or_b32 s100, s100, 0xfc0000
	s_cmp_eq_u32 s101, 8
	s_cselect_b32 s100, 0x3f6da658, s100
	s_cmp_eq_u32 s101, 9
	s_cselect_b32 s100, 0x3f7de75c, s100
.Lemi_loop:
	s_and_b32 s98, s100, 63
	s_lshr_b32 s100, s100, 6
	s_cmp_eq_u32 s98, 63
	s_cbranch_scc1 .Lemi_done
	s_bfe_u32 s4, s98, 0x10002
	s_lshl_b32 s5, s4, 6
	v_writelane_b32 v254, s5, 60
	s_lshl_b32 s5, s4, 2
	v_writelane_b32 v254, s5, 61
	s_and_b32 s6, s85, 7
	s_lshl_b32 s7, s6, 8
	s_bfe_u32 s5, s98, 0x10003
	s_lshl_b32 s5, s5, 11
	s_or_b32 s7, s7, s5
	v_writelane_b32 v254, s7, 62
	s_and_b32 s5, s98, 3
	s_lshl_b32 s5, s5, 6
	s_or_b32 s5, s7, s5
	v_writelane_b32 v254, s5, 63
	s_add_i32 s8, s98, 0x1ffffff0
	s_and_b32 s8, s8, 0x1ffffff8
	s_and_b32 s9, s98, 4
	s_and_b32 s10, s98, 3
	s_mov_b32 s96, s10
	s_or_b32 s11, s8, s6
	s_lshl_b32 s11, s11, 3
	s_or_b32 s11, s11, s9
	s_or_b32 s11, s11, s10
	s_lshl_b32 s11, s11, 5
	s_and_b32 s12, s11, 0x7fffff80
	s_movk_i32 s13, 0x800
	s_mov_b32 s9, 0x7ffff800
	s_cmp_lt_u32 s8, 16
	s_cselect_b32 s13, 0x100, s13
	s_cselect_b32 s8, 0xf00, s9
	v_writelane_b32 v254, s13, 51
	s_and_b32 s8, s11, s8
	v_writelane_b32 v254, s12, 52
	v_writelane_b32 v254, s8, 53
	s_lshl_b32 s13, s10, 15
	s_sub_i32 s8, s12, s8
	v_writelane_b32 v254, s13, 54
	v_writelane_b32 v254, s8, 55
	s_add_i32 s8, s8, -8
	v_writelane_b32 v254, s8, 56
	s_lshl_b32 s8, s10, 7
	v_writelane_b32 v254, s8, 57
	s_lshl_b32 s8, s10, 1
	v_writelane_b32 v254, s8, 58
	s_lshl_b32 s20, s86, 3
	s_lshl_b32 s68, s86, 9
	s_lshl_b64 s[88:89], s[68:69], 2
	v_readlane_b32 s42, v254, 6
	v_readlane_b32 s43, v254, 7
	s_nop 0
	s_add_u32 s90, s42, s88
	s_addc_u32 s91, s43, s89
	s_waitcnt vmcnt(0) lgkmcnt(0)
	s_barrier
	s_cmp_lt_u32 s98, 16
	s_cbranch_scc1 .Lemi_ctx_entry
	s_branch .Lemi_pool_entry
.Lemi_ret:
	s_branch .Lemi_loop
.Lemi_done:
	s_lshr_b32 s98, s85, 3
	s_bfe_u32 s4, s98, 0x10002
	s_lshl_b32 s5, s4, 6
	v_writelane_b32 v254, s5, 60
	s_lshl_b32 s5, s4, 2
	v_writelane_b32 v254, s5, 61
	s_and_b32 s6, s85, 7
	s_lshl_b32 s7, s6, 8
	s_bfe_u32 s5, s98, 0x10003
	s_lshl_b32 s5, s5, 11
	s_or_b32 s7, s7, s5
	v_writelane_b32 v254, s7, 62
	s_and_b32 s5, s98, 3
	s_lshl_b32 s5, s5, 6
	s_or_b32 s5, s7, s5
	v_writelane_b32 v254, s5, 63
	s_add_i32 s8, s98, 0x1ffffff0
	s_and_b32 s8, s8, 0x1ffffff8
	s_and_b32 s9, s98, 4
	s_and_b32 s10, s98, 3
	s_mov_b32 s96, s10
	s_or_b32 s11, s8, s6
	s_lshl_b32 s11, s11, 3
	s_or_b32 s11, s11, s9
	s_or_b32 s11, s11, s10
	s_lshl_b32 s11, s11, 5
	s_and_b32 s12, s11, 0x7fffff80
	s_movk_i32 s13, 0x800
	s_mov_b32 s9, 0x7ffff800
	s_cmp_lt_u32 s8, 16
	s_cselect_b32 s13, 0x100, s13
	s_cselect_b32 s8, 0xf00, s9
	v_writelane_b32 v254, s13, 51
	s_and_b32 s8, s11, s8
	v_writelane_b32 v254, s12, 52
	v_writelane_b32 v254, s8, 53
	s_lshl_b32 s13, s10, 15
	s_sub_i32 s8, s12, s8
	v_writelane_b32 v254, s13, 54
	v_writelane_b32 v254, s8, 55
	s_add_i32 s8, s8, -8
	v_writelane_b32 v254, s8, 56
	s_lshl_b32 s8, s10, 7
	v_writelane_b32 v254, s8, 57
	s_lshl_b32 s8, s10, 1
	v_writelane_b32 v254, s8, 58
	s_mov_b32 s99, 0

.LBB0_395:
	s_or_b64 exec, exec, s[4:5]
	v_mov_b32_e32 v0, 0x23808
	ds_read_b32 v0, v0
	s_waitcnt lgkmcnt(0)
	v_readfirstlane_b32 s4, v0
	s_cmp_lg_u32 s4, 0
	s_cbranch_scc1 .LBB0_444
	v_readlane_b32 s4, v254, 49
	v_readlane_b32 s5, v254, 50
	s_mov_b64 s[0:1], -1
	s_and_b64 vcc, exec, s[4:5]
	s_waitcnt lgkmcnt(0)
	s_barrier
	s_cbranch_vccz .LBB0_430
.Lemi_pool_entry:
	s_mov_b64 s[0:1], 0x697b000
	s_mov_b64 s[94:95], 0x9f7b000
	s_mov_b64 s[92:93], 0xb89b000
	s_mov_b64 s[54:55], 0x1a00000
	v_mbcnt_lo_u32_b32 v132, -1, 0
	v_mbcnt_hi_u32_b32 v132, -1, v132
	s_add_u32 s52, s28, s0
	v_add_u32_e32 v21, s3, v132
	v_ashrrev_i32_e32 v22, 4, v21
	v_readlane_b32 s0, v254, 56
	v_readlane_b32 s4, v254, 51
	v_lshlrev_b32_e32 v0, 3, v132
	v_add_u32_e32 v1, s0, v22
	s_movk_i32 s0, 0x900
	v_cmp_gt_i32_e32 vcc, s0, v21
	v_cmp_gt_i32_e64 s[4:5], s4, v1
	s_addc_u32 s53, s29, s1
	v_and_b32_e32 v2, 0x78, v0
	v_cmp_lt_i32_e64 s[0:1], -1, v1
	s_and_b64 s[4:5], vcc, s[4:5]
	s_and_b64 s[4:5], s[4:5], s[0:1]
	v_mov_b32_e32 v0, 0
	v_lshlrev_b32_e32 v198, 1, v2
	v_mov_b32_e32 v4, 0
	v_mov_b32_e32 v5, 0
	v_mov_b32_e32 v6, 0
	v_mov_b32_e32 v7, 0
	s_and_saveexec_b64 s[0:1], s[4:5]
	s_cbranch_execz .LBB0_398
	v_readlane_b32 s4, v254, 53
	v_mov_b64_e32 v[2:3], s[52:53]
	s_nop 0
	v_add_u32_e32 v1, s4, v1
	v_mad_u64_u32 v[2:3], s[4:5], v1, s62, v[2:3]
	v_readlane_b32 s4, v254, 57
	s_lshl_b32 s68, s4, 1
	v_lshl_add_u64 v[2:3], v[2:3], 0, s[68:69]
	v_lshl_add_u64 v[2:3], v[2:3], 0, v[198:199]
	global_load_dwordx4 v[4:7], v[2:3], off offset:2560

.LBB0_429:
	s_or_b64 exec, exec, s[0:1]
	s_mov_b64 s[0:1], 0
	s_cmp_eq_u32 s99, 1
	s_cbranch_scc1 .Lemi_ret

.Lemi_ctx_entry:
	s_mov_b64 s[0:1], 0x697b000
	s_mov_b64 s[6:7], 0x9f7b000
	s_mov_b64 s[4:5], 0xb83b000
	v_mbcnt_lo_u32_b32 v19, -1, 0
	v_mbcnt_hi_u32_b32 v19, -1, v19
	s_add_u32 s0, s28, s0
	v_add_u32_e32 v26, s3, v19
	v_ashrrev_i32_e32 v27, 3, v26
	s_addc_u32 s1, s29, s1
	v_readlane_b32 s10, v254, 62
	v_readlane_b32 s8, v254, 60
	v_and_b32_e32 v30, 7, v19
	v_lshlrev_b32_e32 v18, 4, v30
	s_lshl_b32 s68, s8, 1
	s_waitcnt lgkmcnt(0)
	v_add_u32_e32 v33, s10, v27
	v_mov_b64_e32 v[34:35], s[0:1]
	v_mad_i64_i32 v[34:35], s[10:11], v33, s62, v[34:35]
	v_lshlrev_b32_e32 v33, 4, v19
	v_lshl_add_u64 v[34:35], v[34:35], 0, s[68:69]
	v_and_b32_e32 v198, 0x70, v33
	v_lshl_add_u64 v[38:39], v[34:35], 0, v[198:199]
	s_mov_b64 s[8:9], 0x48000
	v_lshl_add_u64 v[40:41], v[38:39], 0, s[8:9]
	v_lshl_add_u64 v[42:43], v[40:41], 0, s[8:9]
	v_lshl_add_u64 v[44:45], v[42:43], 0, s[8:9]
	global_load_dwordx4 v[202:205], v[38:39], off offset:1024
	global_load_dwordx4 v[218:221], v[38:39], off offset:1280
	global_load_dwordx4 v[206:209], v[40:41], off offset:1024
	global_load_dwordx4 v[222:225], v[40:41], off offset:1280
	global_load_dwordx4 v[210:213], v[42:43], off offset:1024
	global_load_dwordx4 v[226:229], v[42:43], off offset:1280
	global_load_dwordx4 v[214:217], v[44:45], off offset:1024
	global_load_dwordx4 v[230:233], v[44:45], off offset:1280
	s_movk_i32 s8, 0x1430
	v_mad_u32_u24 v30, v30, s8, v18
	v_lshrrev_b32_e32 v0, 6, v26
	v_readlane_b32 s8, v254, 61
	v_and_b32_e32 v6, 31, v19
	v_and_b32_e32 v1, 0xffffffe0, v27
	v_and_or_b32 v129, v0, 3, s8
	v_readlane_b32 s8, v254, 63
	v_bfe_u32 v7, v19, 5, 1
	v_lshlrev_b32_e32 v198, 7, v129
	v_or_b32_e32 v0, s8, v6
	v_add_u32_e32 v112, v0, v1
	v_mov_b64_e32 v[0:1], s[0:1]
	v_mad_i64_i32 v[0:1], s[0:1], v112, s62, v[0:1]
	v_lshl_add_u64 v[0:1], v[0:1], 0, v[198:199]
	v_lshlrev_b32_e32 v2, 4, v7
	v_mov_b32_e32 v3, v199
	v_lshl_add_u64 v[4:5], v[0:1], 0, v[2:3]
	v_lshlrev_b32_e32 v198, 3, v7
	global_load_dwordx4 v[96:99], v[4:5], off
	global_load_dwordx4 v[100:103], v[4:5], off offset:32
	global_load_dwordx4 v[104:107], v[4:5], off offset:64
	global_load_dwordx4 v[108:111], v[4:5], off offset:96
	v_lshlrev_b32_e32 v4, 8, v129
	v_mov_b32_e32 v5, v199
	v_lshl_add_u64 v[0:1], v[0:1], 0, v[198:199]
	v_lshl_add_u64 v[4:5], s[90:91], 0, v[4:5]
	v_lshl_add_u64 v[4:5], v[4:5], 0, v[2:3]
	global_load_dwordx2 v[130:131], v[0:1], off offset:1536
	global_load_dwordx4 v[92:95], v[4:5], off
	global_load_dwordx2 v[126:127], v[0:1], off offset:1552
	global_load_dwordx4 v[88:91], v[4:5], off offset:32
	global_load_dwordx2 v[124:125], v[0:1], off offset:1568
	global_load_dwordx4 v[84:87], v[4:5], off offset:64
	global_load_dwordx2 v[122:123], v[0:1], off offset:1584
	global_load_dwordx4 v[80:83], v[4:5], off offset:96
	global_load_dwordx2 v[120:121], v[0:1], off offset:1600
	global_load_dwordx4 v[76:79], v[4:5], off offset:128
	global_load_dwordx2 v[118:119], v[0:1], off offset:1616
	global_load_dwordx4 v[72:75], v[4:5], off offset:160
	global_load_dwordx2 v[116:117], v[0:1], off offset:1632
	global_load_dwordx4 v[68:71], v[4:5], off offset:192
	global_load_dwordx2 v[114:115], v[0:1], off offset:1648
	global_load_dwordx4 v[64:67], v[4:5], off offset:224
	v_readlane_b32 s36, v254, 0
	v_or_b32_e32 v0, s20, v129
	v_mov_b32_e32 v1, v199
	v_readlane_b32 s40, v254, 4
	v_readlane_b32 s41, v254, 5
	v_cmp_eq_u32_e32 vcc, 0, v7
	v_mov_b32_e32 v16, 0
	v_lshl_add_u64 v[0:1], v[0:1], 2, s[40:41]
	global_load_dword v0, v[0:1], off
	s_waitcnt vmcnt(21)
	v_mad_u32_u24 v42, v27, s2, v18
	v_mul_u32_u24_e32 v33, 0xc0, v27
	v_add_u32_e32 v33, v33, v18
	v_add_u32_e32 v33, 0xb400, v33
	ds_write_b128 v42, v[202:205]
	ds_write_b128 v33, v[218:221]
	ds_write_b128 v42, v[206:209] offset:9216
	ds_write_b128 v33, v[222:225] offset:12288
	ds_write_b128 v42, v[210:213] offset:18432
	ds_write_b128 v33, v[226:229] offset:24576
	ds_write_b128 v42, v[214:217] offset:27648
	ds_write_b128 v33, v[230:233] offset:36864
	v_bfe_u32 v34, v19, 2, 2
	v_mul_u32_u24_e32 v235, 0xc0, v34
	v_lshrrev_b32_e32 v34, 5, v19
	v_lshl_add_u32 v235, v34, 8, v235
	v_lshl_add_u32 v235, v34, 9, v235
	v_bfe_u32 v34, v19, 4, 1
	v_lshl_add_u32 v235, v34, 5, v235
	v_and_b32_e32 v34, 3, v19
	v_lshl_add_u32 v235, v34, 3, v235
	v_and_b32_e32 v1, 64, v251
	v_add_u32_e32 v1, 64, v1
	v_ashrrev_i32_e32 v113, 31, v112
	v_lshlrev_b32_e32 v132, 6, v129
	v_lshlrev_b32_e32 v128, 2, v7
	s_mov_b32 s8, 0
	v_cndmask_b32_e64 v48, 0, 1.0, vcc
	v_mad_u32_u24 v136, v6, s2, v2
	v_mov_b32_e32 v17, v16
	v_mov_b32_e32 v18, v16
	v_mov_b32_e32 v19, v16
	v_mov_b32_e32 v20, v16
	v_mov_b32_e32 v21, v16
	v_mov_b32_e32 v22, v16
	v_mov_b32_e32 v23, v16
	v_mov_b32_e32 v24, v16
	v_mov_b32_e32 v25, v16
	v_mov_b32_e32 v26, v16
	v_mov_b32_e32 v27, v16
	v_mov_b32_e32 v28, v16
	v_mov_b32_e32 v29, v16
	v_mov_b32_e32 v30, v16
	v_mov_b32_e32 v31, v16
	v_mov_b32_e32 v2, v16
	v_mov_b32_e32 v3, v16
	v_mov_b32_e32 v4, v16
	v_mov_b32_e32 v5, v16
	v_mov_b32_e32 v7, v16
	v_mov_b32_e32 v8, v16
	v_mov_b32_e32 v9, v16
	v_mov_b32_e32 v10, v16
	v_mov_b32_e32 v11, v16
	v_mov_b32_e32 v12, v16
	v_mov_b32_e32 v13, v16
	v_mov_b32_e32 v14, v16
	v_mov_b32_e32 v15, v16
	v_readlane_b32 s37, v254, 1
	v_readlane_b32 s38, v254, 2
	v_readlane_b32 s39, v254, 3
	v_readlane_b32 s42, v254, 6
	v_readlane_b32 s43, v254, 7
	v_readlane_b32 s44, v254, 8
	v_readlane_b32 s45, v254, 9
	v_readlane_b32 s46, v254, 10
	v_readlane_b32 s47, v254, 11
	v_readlane_b32 s48, v254, 12
	v_readlane_b32 s49, v254, 13
	v_readlane_b32 s50, v254, 14
	v_readlane_b32 s51, v254, 15
	s_waitcnt lgkmcnt(0)
	s_barrier
	s_waitcnt vmcnt(0)
	v_mul_f32_e32 v137, 0x3fb8aa3b, v0
	v_xor_b32_e32 v0, 32, v251
	v_cmp_lt_i32_e64 s[0:1], v0, v1
	v_mov_b32_e32 v1, v16
	s_nop 0
	v_cndmask_b32_e64 v0, v251, v0, s[0:1]
	s_movk_i32 s0, 0x288
	v_lshlrev_b32_e32 v133, 2, v0
	v_mad_u32_u24 v135, v6, s0, v198
	v_mov_b32_e32 v0, v16
	v_mov_b32_e32 v6, v16
	v_mov_b32_e32 v244, v48
	s_mov_b32 s21, 4
	v_mov_b32_e32 v234, v235
	ds_read_b128 v[202:205], v136
	ds_read_b128 v[206:209], v136 offset:32
	ds_read_b128 v[210:213], v136 offset:64
	ds_read_b128 v[214:217], v136 offset:96
	ds_read_b128 v[218:221], v136 offset:4608
	ds_read_b128 v[222:225], v136 offset:4640
	ds_read_b128 v[226:229], v136 offset:4672
	ds_read_b128 v[230:233], v136 offset:4704
	v_add_u32_e32 v136, 0x2400, v136

.LBB0_443:
	s_or_b64 exec, exec, s[0:1]
	s_cmp_eq_u32 s99, 1
	s_cbranch_scc1 .Lemi_ret

	.amdhsa_kernel _Z14fwd_megakernel6Params
		.amdhsa_group_segment_fixed_size 145424
		.amdhsa_private_segment_fixed_size 0
		.amdhsa_kernarg_size 408
		.amdhsa_user_sgpr_count 2
		.amdhsa_user_sgpr_dispatch_ptr 0
		.amdhsa_user_sgpr_queue_ptr 0
		.amdhsa_user_sgpr_kernarg_segment_ptr 1
		.amdhsa_user_sgpr_dispatch_id 0
		.amdhsa_user_sgpr_kernarg_preload_length 0
		.amdhsa_user_sgpr_kernarg_preload_offset 0
		.amdhsa_user_sgpr_private_segment_size 0
		.amdhsa_uses_dynamic_stack 0
		.amdhsa_enable_private_segment 0
		.amdhsa_system_sgpr_workgroup_id_x 1
		.amdhsa_system_sgpr_workgroup_id_y 0
		.amdhsa_system_sgpr_workgroup_id_z 0
		.amdhsa_system_sgpr_workgroup_info 0
		.amdhsa_system_vgpr_workitem_id 2
		.amdhsa_next_free_vgpr 256
		.amdhsa_next_free_sgpr 102
		.amdhsa_accum_offset 256
		.amdhsa_reserve_vcc 1
		.amdhsa_float_round_mode_32 0
		.amdhsa_float_round_mode_16_64 0
		.amdhsa_float_denorm_mode_32 3
		.amdhsa_float_denorm_mode_16_64 3
		.amdhsa_dx10_clamp 1
		.amdhsa_ieee_mode 1
		.amdhsa_fp16_overflow 0
		.amdhsa_tg_split 0
		.amdhsa_exception_fp_ieee_invalid_op 0
		.amdhsa_exception_fp_denorm_src 0
		.amdhsa_exception_fp_ieee_div_zero 0
		.amdhsa_exception_fp_ieee_overflow 0
		.amdhsa_exception_fp_ieee_underflow 0
		.amdhsa_exception_fp_ieee_inexact 0
		.amdhsa_exception_int_div_zero 0
	.end_amdhsa_kernel

amdhsa.kernels:
  - .agpr_count:     0
    .args:
      - .offset:         0
        .size:           152
        .value_kind:     by_value
      - .offset:         152
        .size:           4
        .value_kind:     hidden_block_count_x
      - .offset:         156
        .size:           4
        .value_kind:     hidden_block_count_y
      - .offset:         160
        .size:           4
        .value_kind:     hidden_block_count_z
      - .offset:         164
        .size:           2
        .value_kind:     hidden_group_size_x
      - .offset:         166
        .size:           2
        .value_kind:     hidden_group_size_y
      - .offset:         168
        .size:           2
        .value_kind:     hidden_group_size_z
      - .offset:         170
        .size:           2
        .value_kind:     hidden_remainder_x
      - .offset:         172
        .size:           2
        .value_kind:     hidden_remainder_y
      - .offset:         174
        .size:           2
        .value_kind:     hidden_remainder_z
      - .offset:         192
        .size:           8
        .value_kind:     hidden_global_offset_x
      - .offset:         200
        .size:           8
        .value_kind:     hidden_global_offset_y
      - .offset:         208
        .size:           8
        .value_kind:     hidden_global_offset_z
      - .offset:         216
        .size:           2
        .value_kind:     hidden_grid_dims
      - .offset:         240
        .size:           8
        .value_kind:     hidden_multigrid_sync_arg
    .group_segment_fixed_size: 145424
    .kernarg_segment_align: 8
    .kernarg_segment_size: 408
    .language:       OpenCL C
    .language_version:
      - 2
      - 0
    .max_flat_workgroup_size: 512
    .name:           _Z14fwd_megakernel6Params
    .private_segment_fixed_size: 0
    .sgpr_count:     108
    .sgpr_spill_count: 104
    .symbol:         _Z14fwd_megakernel6Params.kd
    .uniform_work_group_size: 1
    .uses_dynamic_stack: false
    .vgpr_count:     256
    .vgpr_spill_count: 0
    .wavefront_size: 64
